# final: ring GEMM loops with interleaved LDS reads, GEMM2 batched epilogue, attention mask-free path, slice-pass expert phase (dummy queue-slot load uses its own register)
# baseline (speedup 1.0000x reference)
.LBB0_217:
	s_or_b64 exec, exec, s[4:5]
	s_barrier
	v_readlane_b32 s2, v242, 0
	v_ashrrev_i32_e32 v0, 6, v186
	s_nop 0
	v_add_u32_e32 v0, s2, v0
	s_nop 0
	v_readfirstlane_b32 s4, v0
	s_mov_b32 s5, s76
	s_cmpk_gt_i32 s4, 0x3fff
	s_cbranch_scc1 .LBB0_226
	s_load_dwordx2 s[28:29], s[0:1], 0xb0
	s_load_dwordx2 s[26:27], s[0:1], 0xc0
	s_load_dwordx4 s[16:19], s[0:1], 0xf0
	s_load_dwordx2 s[10:11], s[0:1], 0x100
	s_load_dwordx4 s[20:23], s[0:1], 0x108
	s_load_dwordx4 s[12:15], s[0:1], 0x148
	s_load_dwordx2 s[24:25], s[0:1], 0x158
	v_and_b32_e32 v228, 63, v186
	v_and_b32_e32 v212, 7, v228
	v_lshrrev_b32_e32 v213, 3, v228
	v_lshlrev_b32_e32 v220, 4, v212
	v_mul_u32_u24_e32 v232, 24, v212
	v_lshlrev_b32_e32 v224, 3, v212
	v_sub_u32_e32 v221, 0x80, v224
	v_bfrev_b32_e32 v214, v213
	v_lshrrev_b32_e32 v214, 29, v214
	v_lshl_add_u32 v225, v214, 9, v224
	v_lshl_add_u32 v226, v214, 10, v220
	v_xor_b32_e32 v227, 32, v228
	v_lshlrev_b32_e32 v227, 2, v227
	v_mov_b32_e32 v231, 0
	v_lshrrev_b32_e32 v215, 6, v186
	s_nop 0
	v_readfirstlane_b32 s64, v215
	s_lshl_b32 s64, s64, 13
	s_add_i32 s64, s64, 16
	v_lshl_add_u32 v222, v228, 3, s64
	v_lshl_add_u32 v223, v213, 6, s64
	v_lshl_add_u32 v230, v228, 2, s64
	v_add_u32_e32 v229, 0x1000, v223
	s_mov_b32 s40, 0xaaaaaaaa
	s_mov_b32 s41, 0xaaaaaaaa
	s_mov_b32 s42, 0xcccccccc
	s_mov_b32 s43, 0xcccccccc
	s_mov_b32 s44, 0xf0f0f0f0
	s_mov_b32 s45, 0xf0f0f0f0
	s_mov_b32 s46, 0xff00ff00
	s_mov_b32 s47, 0xff00ff00
	s_mov_b32 s48, 0xffff0000
	s_mov_b32 s49, 0xffff0000
	s_mov_b32 s50, 0
	s_mov_b32 s51, -1
	s_movk_i32 s52, 0xc0
	s_mov_b32 s66, 0x378e98ab
	s_mov_b32 s67, 0xb9c68948
	s_mov_b32 s68, 0x3b7cd369
	s_mov_b32 s69, 0xbcc618b2
	s_mov_b32 s70, 0x3dda74e4
	s_mov_b32 s71, 0x3f228afd
	s_mov_b32 s72, 0x3e03c728
	s_mov_b32 s73, 0xbfb8aa3b
	s_mov_b32 s74, 0x42ce8ed0
	s_mov_b32 s75, 0xc2b17218
	s_mov_b32 s76, 0x3ba10414
	s_mov_b32 s77, 0x7fffffff
	s_lshr_b32 s91, s64, 13
	s_mov_b32 s6, s4
	s_waitcnt lgkmcnt(0)

.Lex_ufirst:
	ds_write_b64 v219, v[192:193]
	s_cmp_lt_u32 s8, 8
	s_cbranch_scc1 .Lex_uloop
	s_waitcnt vmcnt(0) lgkmcnt(0)
	ds_read_b64 v[96:97], v222 offset:4096
	ds_read_b64 v[98:99], v222 offset:0
	ds_read_b64 v[108:109], v222 offset:4608
	ds_read_b64 v[110:111], v222 offset:512
	ds_read_b64 v[120:121], v222 offset:5120
	ds_read_b64 v[122:123], v222 offset:1024
	ds_read_b64 v[132:133], v222 offset:5632
	ds_read_b64 v[134:135], v222 offset:1536
	ds_read_b64 v[144:145], v222 offset:6144
	ds_read_b64 v[146:147], v222 offset:2048
	ds_read_b64 v[156:157], v222 offset:6656
	ds_read_b64 v[158:159], v222 offset:2560
	ds_read_b64 v[168:169], v222 offset:7168
	ds_read_b64 v[170:171], v222 offset:3072
	ds_read_b64 v[180:181], v222 offset:7680
	ds_read_b64 v[182:183], v222 offset:3584
	s_waitcnt lgkmcnt(0)
	s_movk_i32 s36, 0
	s_mul_i32 s37, s36, s5
	s_add_i32 s37, s37, s6
	s_min_u32 s37, s37, 0x3fff
	s_lshl_b32 s37, s37, 9
	s_add_u32 s82, s14, s37
	s_addc_u32 s83, s15, 0
	v_lshlrev_b32_e32 v219, 3, v228
	global_load_dwordx2 v[100:101], v219, s[82:83]
	v_lshlrev_b32_e32 v217, 2, v98
	v_lshlrev_b32_e32 v218, 2, v99
	global_load_dword v102, v217, s[20:21]
	global_load_dword v103, v218, s[20:21]
	global_load_dword v104, v217, s[22:23]
	global_load_dword v105, v218, s[22:23]
	s_movk_i32 s36, 1
	s_mul_i32 s37, s36, s5
	s_add_i32 s37, s37, s6
	s_min_u32 s37, s37, 0x3fff
	s_lshl_b32 s37, s37, 9
	s_add_u32 s82, s14, s37
	s_addc_u32 s83, s15, 0
	v_lshlrev_b32_e32 v219, 3, v228
	global_load_dwordx2 v[112:113], v219, s[82:83]
	v_lshlrev_b32_e32 v217, 2, v110
	v_lshlrev_b32_e32 v218, 2, v111
	global_load_dword v114, v217, s[20:21]
	global_load_dword v115, v218, s[20:21]
	global_load_dword v116, v217, s[22:23]
	global_load_dword v117, v218, s[22:23]
	s_movk_i32 s36, 2
	s_mul_i32 s37, s36, s5
	s_add_i32 s37, s37, s6
	s_min_u32 s37, s37, 0x3fff
	s_lshl_b32 s37, s37, 9
	s_add_u32 s82, s14, s37
	s_addc_u32 s83, s15, 0
	v_lshlrev_b32_e32 v219, 3, v228
	global_load_dwordx2 v[124:125], v219, s[82:83]
	v_lshlrev_b32_e32 v217, 2, v122
	v_lshlrev_b32_e32 v218, 2, v123
	global_load_dword v126, v217, s[20:21]
	global_load_dword v127, v218, s[20:21]
	global_load_dword v128, v217, s[22:23]
	global_load_dword v129, v218, s[22:23]
	s_movk_i32 s36, 3
	s_mul_i32 s37, s36, s5
	s_add_i32 s37, s37, s6
	s_min_u32 s37, s37, 0x3fff
	s_lshl_b32 s37, s37, 9
	s_add_u32 s82, s14, s37
	s_addc_u32 s83, s15, 0
	v_lshlrev_b32_e32 v219, 3, v228
	global_load_dwordx2 v[136:137], v219, s[82:83]
	v_lshlrev_b32_e32 v217, 2, v134
	v_lshlrev_b32_e32 v218, 2, v135
	global_load_dword v138, v217, s[20:21]
	global_load_dword v139, v218, s[20:21]
	global_load_dword v140, v217, s[22:23]
	global_load_dword v141, v218, s[22:23]
	s_movk_i32 s36, 4
	s_mul_i32 s37, s36, s5
	s_add_i32 s37, s37, s6
	s_min_u32 s37, s37, 0x3fff
	s_lshl_b32 s37, s37, 9
	s_add_u32 s82, s14, s37
	s_addc_u32 s83, s15, 0
	v_lshlrev_b32_e32 v219, 3, v228
	global_load_dwordx2 v[148:149], v219, s[82:83]
	v_lshlrev_b32_e32 v217, 2, v146
	v_lshlrev_b32_e32 v218, 2, v147
	global_load_dword v150, v217, s[20:21]
	global_load_dword v151, v218, s[20:21]
	global_load_dword v152, v217, s[22:23]
	global_load_dword v153, v218, s[22:23]
	s_movk_i32 s36, 5
	s_mul_i32 s37, s36, s5
	s_add_i32 s37, s37, s6
	s_min_u32 s37, s37, 0x3fff
	s_lshl_b32 s37, s37, 9
	s_add_u32 s82, s14, s37
	s_addc_u32 s83, s15, 0
	v_lshlrev_b32_e32 v219, 3, v228
	global_load_dwordx2 v[160:161], v219, s[82:83]
	v_lshlrev_b32_e32 v217, 2, v158
	v_lshlrev_b32_e32 v218, 2, v159
	global_load_dword v162, v217, s[20:21]
	global_load_dword v163, v218, s[20:21]
	global_load_dword v164, v217, s[22:23]
	global_load_dword v165, v218, s[22:23]
	s_movk_i32 s36, 6
	s_mul_i32 s37, s36, s5
	s_add_i32 s37, s37, s6
	s_min_u32 s37, s37, 0x3fff
	s_lshl_b32 s37, s37, 9
	s_add_u32 s82, s14, s37
	s_addc_u32 s83, s15, 0
	v_lshlrev_b32_e32 v219, 3, v228
	global_load_dwordx2 v[172:173], v219, s[82:83]
	v_lshlrev_b32_e32 v217, 2, v170
	v_lshlrev_b32_e32 v218, 2, v171
	global_load_dword v174, v217, s[20:21]
	global_load_dword v175, v218, s[20:21]
	global_load_dword v176, v217, s[22:23]
	global_load_dword v177, v218, s[22:23]
	s_movk_i32 s36, 7
	s_mul_i32 s37, s36, s5
	s_add_i32 s37, s37, s6
	s_min_u32 s37, s37, 0x3fff
	s_lshl_b32 s37, s37, 9
	s_add_u32 s82, s14, s37
	s_addc_u32 s83, s15, 0
	v_lshlrev_b32_e32 v219, 3, v228
	global_load_dwordx2 v[184:185], v219, s[82:83]
	v_lshlrev_b32_e32 v217, 2, v182
	v_lshlrev_b32_e32 v218, 2, v183
	global_load_dword v186, v217, s[20:21]
	global_load_dword v187, v218, s[20:21]
	global_load_dword v188, v217, s[22:23]
	global_load_dword v189, v218, s[22:23]
	s_waitcnt vmcnt(0)
	v_mul_f32_e32 v96, v102, v96
	v_mul_f32_e32 v0, 0x3f3504f3, v96
	v_mov_b32_e32 v6, s67
	v_fma_f32 v2, |v0|, s66, v6
	v_fma_f32 v2, |v0|, v2, s68
	v_fma_f32 v2, |v0|, v2, s69
	v_fma_f32 v2, |v0|, v2, s70
	v_fma_f32 v2, |v0|, v2, s71
	v_fma_f32 v2, |v0|, v2, s72
	v_fma_f32 v2, |v0|, v2, |v0|
	v_mul_f32_e32 v4, 0xbfb8aa3b, v2
	v_fma_f32 v5, v2, s73, -v4
	v_rndne_f32_e32 v6, v4
	v_fmac_f32_e32 v5, 0xb2a5705f, v2
	v_sub_f32_e32 v4, v4, v6
	v_add_f32_e32 v4, v4, v5
	v_cvt_i32_f32_e32 v5, v6
	v_exp_f32_e32 v4, v4
	v_cmp_nlt_f32_e64 s[82:83], s74, v2
	v_ldexp_f32 v4, v4, v5
	s_nop 0
	v_cndmask_b32_e64 v4, 0, v4, s[82:83]
	v_cmp_ngt_f32_e64 s[82:83], s75, v2
	v_mov_b32_e32 v6, 0x7f800000
	s_nop 0
	v_cndmask_b32_e64 v3, v6, v4, s[82:83]
	v_sub_f32_e32 v3, 1.0, v3
	v_mul_f32_e32 v4, v0, v0
	v_mov_b32_e32 v6, s76
	v_fmamk_f32 v5, v4, 0xba1345e1, v6
	v_fmaak_f32 v5, v4, v5, 0xbcdac9b8
	v_fmaak_f32 v5, v4, v5, 0x3de703be
	v_fmaak_f32 v5, v4, v5, 0xbec09330
	v_fmaak_f32 v4, v4, v5, 0x3e0375d0
	v_fma_f32 v7, |v0|, v4, |v0|
	v_cmp_nlt_f32_e64 s[82:83], |v0|, 1.0
	s_nop 1
	v_cndmask_b32_e64 v3, v7, v3, s[82:83]
	v_bfi_b32 v3, s77, v3, v0
	v_mul_f32_e32 v96, 0.5, v96
	v_add_f32_e32 v3, 1.0, v3
	v_mul_f32_e32 v96, v96, v3
	v_mul_f32_e32 v96, v96, v100
	v_mul_f32_e32 v96, v104, v96
	v_mul_f32_e32 v97, v103, v97
	v_mul_f32_e32 v0, 0x3f3504f3, v97
	v_mov_b32_e32 v6, s67
	v_fma_f32 v2, |v0|, s66, v6
	v_fma_f32 v2, |v0|, v2, s68
	v_fma_f32 v2, |v0|, v2, s69
	v_fma_f32 v2, |v0|, v2, s70
	v_fma_f32 v2, |v0|, v2, s71
	v_fma_f32 v2, |v0|, v2, s72
	v_fma_f32 v2, |v0|, v2, |v0|
	v_mul_f32_e32 v4, 0xbfb8aa3b, v2
	v_fma_f32 v5, v2, s73, -v4
	v_rndne_f32_e32 v6, v4
	v_fmac_f32_e32 v5, 0xb2a5705f, v2
	v_sub_f32_e32 v4, v4, v6
	v_add_f32_e32 v4, v4, v5
	v_cvt_i32_f32_e32 v5, v6
	v_exp_f32_e32 v4, v4
	v_cmp_nlt_f32_e64 s[82:83], s74, v2
	v_ldexp_f32 v4, v4, v5
	s_nop 0
	v_cndmask_b32_e64 v4, 0, v4, s[82:83]
	v_cmp_ngt_f32_e64 s[82:83], s75, v2
	v_mov_b32_e32 v6, 0x7f800000
	s_nop 0
	v_cndmask_b32_e64 v3, v6, v4, s[82:83]
	v_sub_f32_e32 v3, 1.0, v3
	v_mul_f32_e32 v4, v0, v0
	v_mov_b32_e32 v6, s76
	v_fmamk_f32 v5, v4, 0xba1345e1, v6
	v_fmaak_f32 v5, v4, v5, 0xbcdac9b8
	v_fmaak_f32 v5, v4, v5, 0x3de703be
	v_fmaak_f32 v5, v4, v5, 0xbec09330
	v_fmaak_f32 v4, v4, v5, 0x3e0375d0
	v_fma_f32 v7, |v0|, v4, |v0|
	v_cmp_nlt_f32_e64 s[82:83], |v0|, 1.0
	s_nop 1
	v_cndmask_b32_e64 v3, v7, v3, s[82:83]
	v_bfi_b32 v3, s77, v3, v0
	v_mul_f32_e32 v97, 0.5, v97
	v_add_f32_e32 v3, 1.0, v3
	v_mul_f32_e32 v97, v97, v3
	v_mul_f32_e32 v97, v97, v101
	v_mul_f32_e32 v97, v105, v97
	ds_write_b64 v222, v[96:97] offset:4096
	v_mul_f32_e32 v108, v114, v108
	v_mul_f32_e32 v0, 0x3f3504f3, v108
	v_mov_b32_e32 v6, s67
	v_fma_f32 v2, |v0|, s66, v6
	v_fma_f32 v2, |v0|, v2, s68
	v_fma_f32 v2, |v0|, v2, s69
	v_fma_f32 v2, |v0|, v2, s70
	v_fma_f32 v2, |v0|, v2, s71
	v_fma_f32 v2, |v0|, v2, s72
	v_fma_f32 v2, |v0|, v2, |v0|
	v_mul_f32_e32 v4, 0xbfb8aa3b, v2
	v_fma_f32 v5, v2, s73, -v4
	v_rndne_f32_e32 v6, v4
	v_fmac_f32_e32 v5, 0xb2a5705f, v2
	v_sub_f32_e32 v4, v4, v6
	v_add_f32_e32 v4, v4, v5
	v_cvt_i32_f32_e32 v5, v6
	v_exp_f32_e32 v4, v4
	v_cmp_nlt_f32_e64 s[82:83], s74, v2
	v_ldexp_f32 v4, v4, v5
	s_nop 0
	v_cndmask_b32_e64 v4, 0, v4, s[82:83]
	v_cmp_ngt_f32_e64 s[82:83], s75, v2
	v_mov_b32_e32 v6, 0x7f800000
	s_nop 0
	v_cndmask_b32_e64 v3, v6, v4, s[82:83]
	v_sub_f32_e32 v3, 1.0, v3
	v_mul_f32_e32 v4, v0, v0
	v_mov_b32_e32 v6, s76
	v_fmamk_f32 v5, v4, 0xba1345e1, v6
	v_fmaak_f32 v5, v4, v5, 0xbcdac9b8
	v_fmaak_f32 v5, v4, v5, 0x3de703be
	v_fmaak_f32 v5, v4, v5, 0xbec09330
	v_fmaak_f32 v4, v4, v5, 0x3e0375d0
	v_fma_f32 v7, |v0|, v4, |v0|
	v_cmp_nlt_f32_e64 s[82:83], |v0|, 1.0
	s_nop 1
	v_cndmask_b32_e64 v3, v7, v3, s[82:83]
	v_bfi_b32 v3, s77, v3, v0
	v_mul_f32_e32 v108, 0.5, v108
	v_add_f32_e32 v3, 1.0, v3
	v_mul_f32_e32 v108, v108, v3
	v_mul_f32_e32 v108, v108, v112
	v_mul_f32_e32 v108, v116, v108
	v_mul_f32_e32 v109, v115, v109
	v_mul_f32_e32 v0, 0x3f3504f3, v109
	v_mov_b32_e32 v6, s67
	v_fma_f32 v2, |v0|, s66, v6
	v_fma_f32 v2, |v0|, v2, s68
	v_fma_f32 v2, |v0|, v2, s69
	v_fma_f32 v2, |v0|, v2, s70
	v_fma_f32 v2, |v0|, v2, s71
	v_fma_f32 v2, |v0|, v2, s72
	v_fma_f32 v2, |v0|, v2, |v0|
	v_mul_f32_e32 v4, 0xbfb8aa3b, v2
	v_fma_f32 v5, v2, s73, -v4
	v_rndne_f32_e32 v6, v4
	v_fmac_f32_e32 v5, 0xb2a5705f, v2
	v_sub_f32_e32 v4, v4, v6
	v_add_f32_e32 v4, v4, v5
	v_cvt_i32_f32_e32 v5, v6
	v_exp_f32_e32 v4, v4
	v_cmp_nlt_f32_e64 s[82:83], s74, v2
	v_ldexp_f32 v4, v4, v5
	s_nop 0
	v_cndmask_b32_e64 v4, 0, v4, s[82:83]
	v_cmp_ngt_f32_e64 s[82:83], s75, v2
	v_mov_b32_e32 v6, 0x7f800000
	s_nop 0
	v_cndmask_b32_e64 v3, v6, v4, s[82:83]
	v_sub_f32_e32 v3, 1.0, v3
	v_mul_f32_e32 v4, v0, v0
	v_mov_b32_e32 v6, s76
	v_fmamk_f32 v5, v4, 0xba1345e1, v6
	v_fmaak_f32 v5, v4, v5, 0xbcdac9b8
	v_fmaak_f32 v5, v4, v5, 0x3de703be
	v_fmaak_f32 v5, v4, v5, 0xbec09330
	v_fmaak_f32 v4, v4, v5, 0x3e0375d0
	v_fma_f32 v7, |v0|, v4, |v0|
	v_cmp_nlt_f32_e64 s[82:83], |v0|, 1.0
	s_nop 1
	v_cndmask_b32_e64 v3, v7, v3, s[82:83]
	v_bfi_b32 v3, s77, v3, v0
	v_mul_f32_e32 v109, 0.5, v109
	v_add_f32_e32 v3, 1.0, v3
	v_mul_f32_e32 v109, v109, v3
	v_mul_f32_e32 v109, v109, v113
	v_mul_f32_e32 v109, v117, v109
	ds_write_b64 v222, v[108:109] offset:4608
	v_mul_f32_e32 v120, v126, v120
	v_mul_f32_e32 v0, 0x3f3504f3, v120
	v_mov_b32_e32 v6, s67
	v_fma_f32 v2, |v0|, s66, v6
	v_fma_f32 v2, |v0|, v2, s68
	v_fma_f32 v2, |v0|, v2, s69
	v_fma_f32 v2, |v0|, v2, s70
	v_fma_f32 v2, |v0|, v2, s71
	v_fma_f32 v2, |v0|, v2, s72
	v_fma_f32 v2, |v0|, v2, |v0|
	v_mul_f32_e32 v4, 0xbfb8aa3b, v2
	v_fma_f32 v5, v2, s73, -v4
	v_rndne_f32_e32 v6, v4
	v_fmac_f32_e32 v5, 0xb2a5705f, v2
	v_sub_f32_e32 v4, v4, v6
	v_add_f32_e32 v4, v4, v5
	v_cvt_i32_f32_e32 v5, v6
	v_exp_f32_e32 v4, v4
	v_cmp_nlt_f32_e64 s[82:83], s74, v2
	v_ldexp_f32 v4, v4, v5
	s_nop 0
	v_cndmask_b32_e64 v4, 0, v4, s[82:83]
	v_cmp_ngt_f32_e64 s[82:83], s75, v2
	v_mov_b32_e32 v6, 0x7f800000
	s_nop 0
	v_cndmask_b32_e64 v3, v6, v4, s[82:83]
	v_sub_f32_e32 v3, 1.0, v3
	v_mul_f32_e32 v4, v0, v0
	v_mov_b32_e32 v6, s76
	v_fmamk_f32 v5, v4, 0xba1345e1, v6
	v_fmaak_f32 v5, v4, v5, 0xbcdac9b8
	v_fmaak_f32 v5, v4, v5, 0x3de703be
	v_fmaak_f32 v5, v4, v5, 0xbec09330
	v_fmaak_f32 v4, v4, v5, 0x3e0375d0
	v_fma_f32 v7, |v0|, v4, |v0|
	v_cmp_nlt_f32_e64 s[82:83], |v0|, 1.0
	s_nop 1
	v_cndmask_b32_e64 v3, v7, v3, s[82:83]
	v_bfi_b32 v3, s77, v3, v0
	v_mul_f32_e32 v120, 0.5, v120
	v_add_f32_e32 v3, 1.0, v3
	v_mul_f32_e32 v120, v120, v3
	v_mul_f32_e32 v120, v120, v124
	v_mul_f32_e32 v120, v128, v120
	v_mul_f32_e32 v121, v127, v121
	v_mul_f32_e32 v0, 0x3f3504f3, v121
	v_mov_b32_e32 v6, s67
	v_fma_f32 v2, |v0|, s66, v6
	v_fma_f32 v2, |v0|, v2, s68
	v_fma_f32 v2, |v0|, v2, s69
	v_fma_f32 v2, |v0|, v2, s70
	v_fma_f32 v2, |v0|, v2, s71
	v_fma_f32 v2, |v0|, v2, s72
	v_fma_f32 v2, |v0|, v2, |v0|
	v_mul_f32_e32 v4, 0xbfb8aa3b, v2
	v_fma_f32 v5, v2, s73, -v4
	v_rndne_f32_e32 v6, v4
	v_fmac_f32_e32 v5, 0xb2a5705f, v2
	v_sub_f32_e32 v4, v4, v6
	v_add_f32_e32 v4, v4, v5
	v_cvt_i32_f32_e32 v5, v6
	v_exp_f32_e32 v4, v4
	v_cmp_nlt_f32_e64 s[82:83], s74, v2
	v_ldexp_f32 v4, v4, v5
	s_nop 0
	v_cndmask_b32_e64 v4, 0, v4, s[82:83]
	v_cmp_ngt_f32_e64 s[82:83], s75, v2
	v_mov_b32_e32 v6, 0x7f800000
	s_nop 0
	v_cndmask_b32_e64 v3, v6, v4, s[82:83]
	v_sub_f32_e32 v3, 1.0, v3
	v_mul_f32_e32 v4, v0, v0
	v_mov_b32_e32 v6, s76
	v_fmamk_f32 v5, v4, 0xba1345e1, v6
	v_fmaak_f32 v5, v4, v5, 0xbcdac9b8
	v_fmaak_f32 v5, v4, v5, 0x3de703be
	v_fmaak_f32 v5, v4, v5, 0xbec09330
	v_fmaak_f32 v4, v4, v5, 0x3e0375d0
	v_fma_f32 v7, |v0|, v4, |v0|
	v_cmp_nlt_f32_e64 s[82:83], |v0|, 1.0
	s_nop 1
	v_cndmask_b32_e64 v3, v7, v3, s[82:83]
	v_bfi_b32 v3, s77, v3, v0
	v_mul_f32_e32 v121, 0.5, v121
	v_add_f32_e32 v3, 1.0, v3
	v_mul_f32_e32 v121, v121, v3
	v_mul_f32_e32 v121, v121, v125
	v_mul_f32_e32 v121, v129, v121
	ds_write_b64 v222, v[120:121] offset:5120
	v_mul_f32_e32 v132, v138, v132
	v_mul_f32_e32 v0, 0x3f3504f3, v132
	v_mov_b32_e32 v6, s67
	v_fma_f32 v2, |v0|, s66, v6
	v_fma_f32 v2, |v0|, v2, s68
	v_fma_f32 v2, |v0|, v2, s69
	v_fma_f32 v2, |v0|, v2, s70
	v_fma_f32 v2, |v0|, v2, s71
	v_fma_f32 v2, |v0|, v2, s72
	v_fma_f32 v2, |v0|, v2, |v0|
	v_mul_f32_e32 v4, 0xbfb8aa3b, v2
	v_fma_f32 v5, v2, s73, -v4
	v_rndne_f32_e32 v6, v4
	v_fmac_f32_e32 v5, 0xb2a5705f, v2
	v_sub_f32_e32 v4, v4, v6
	v_add_f32_e32 v4, v4, v5
	v_cvt_i32_f32_e32 v5, v6
	v_exp_f32_e32 v4, v4
	v_cmp_nlt_f32_e64 s[82:83], s74, v2
	v_ldexp_f32 v4, v4, v5
	s_nop 0
	v_cndmask_b32_e64 v4, 0, v4, s[82:83]
	v_cmp_ngt_f32_e64 s[82:83], s75, v2
	v_mov_b32_e32 v6, 0x7f800000
	s_nop 0
	v_cndmask_b32_e64 v3, v6, v4, s[82:83]
	v_sub_f32_e32 v3, 1.0, v3
	v_mul_f32_e32 v4, v0, v0
	v_mov_b32_e32 v6, s76
	v_fmamk_f32 v5, v4, 0xba1345e1, v6
	v_fmaak_f32 v5, v4, v5, 0xbcdac9b8
	v_fmaak_f32 v5, v4, v5, 0x3de703be
	v_fmaak_f32 v5, v4, v5, 0xbec09330
	v_fmaak_f32 v4, v4, v5, 0x3e0375d0
	v_fma_f32 v7, |v0|, v4, |v0|
	v_cmp_nlt_f32_e64 s[82:83], |v0|, 1.0
	s_nop 1
	v_cndmask_b32_e64 v3, v7, v3, s[82:83]
	v_bfi_b32 v3, s77, v3, v0
	v_mul_f32_e32 v132, 0.5, v132
	v_add_f32_e32 v3, 1.0, v3
	v_mul_f32_e32 v132, v132, v3
	v_mul_f32_e32 v132, v132, v136
	v_mul_f32_e32 v132, v140, v132
	v_mul_f32_e32 v133, v139, v133
	v_mul_f32_e32 v0, 0x3f3504f3, v133
	v_mov_b32_e32 v6, s67
	v_fma_f32 v2, |v0|, s66, v6
	v_fma_f32 v2, |v0|, v2, s68
	v_fma_f32 v2, |v0|, v2, s69
	v_fma_f32 v2, |v0|, v2, s70
	v_fma_f32 v2, |v0|, v2, s71
	v_fma_f32 v2, |v0|, v2, s72
	v_fma_f32 v2, |v0|, v2, |v0|
	v_mul_f32_e32 v4, 0xbfb8aa3b, v2
	v_fma_f32 v5, v2, s73, -v4
	v_rndne_f32_e32 v6, v4
	v_fmac_f32_e32 v5, 0xb2a5705f, v2
	v_sub_f32_e32 v4, v4, v6
	v_add_f32_e32 v4, v4, v5
	v_cvt_i32_f32_e32 v5, v6
	v_exp_f32_e32 v4, v4
	v_cmp_nlt_f32_e64 s[82:83], s74, v2
	v_ldexp_f32 v4, v4, v5
	s_nop 0
	v_cndmask_b32_e64 v4, 0, v4, s[82:83]
	v_cmp_ngt_f32_e64 s[82:83], s75, v2
	v_mov_b32_e32 v6, 0x7f800000
	s_nop 0
	v_cndmask_b32_e64 v3, v6, v4, s[82:83]
	v_sub_f32_e32 v3, 1.0, v3
	v_mul_f32_e32 v4, v0, v0
	v_mov_b32_e32 v6, s76
	v_fmamk_f32 v5, v4, 0xba1345e1, v6
	v_fmaak_f32 v5, v4, v5, 0xbcdac9b8
	v_fmaak_f32 v5, v4, v5, 0x3de703be
	v_fmaak_f32 v5, v4, v5, 0xbec09330
	v_fmaak_f32 v4, v4, v5, 0x3e0375d0
	v_fma_f32 v7, |v0|, v4, |v0|
	v_cmp_nlt_f32_e64 s[82:83], |v0|, 1.0
	s_nop 1
	v_cndmask_b32_e64 v3, v7, v3, s[82:83]
	v_bfi_b32 v3, s77, v3, v0
	v_mul_f32_e32 v133, 0.5, v133
	v_add_f32_e32 v3, 1.0, v3
	v_mul_f32_e32 v133, v133, v3
	v_mul_f32_e32 v133, v133, v137
	v_mul_f32_e32 v133, v141, v133
	ds_write_b64 v222, v[132:133] offset:5632
	v_mul_f32_e32 v144, v150, v144
	v_mul_f32_e32 v0, 0x3f3504f3, v144
	v_mov_b32_e32 v6, s67
	v_fma_f32 v2, |v0|, s66, v6
	v_fma_f32 v2, |v0|, v2, s68
	v_fma_f32 v2, |v0|, v2, s69
	v_fma_f32 v2, |v0|, v2, s70
	v_fma_f32 v2, |v0|, v2, s71
	v_fma_f32 v2, |v0|, v2, s72
	v_fma_f32 v2, |v0|, v2, |v0|
	v_mul_f32_e32 v4, 0xbfb8aa3b, v2
	v_fma_f32 v5, v2, s73, -v4
	v_rndne_f32_e32 v6, v4
	v_fmac_f32_e32 v5, 0xb2a5705f, v2
	v_sub_f32_e32 v4, v4, v6
	v_add_f32_e32 v4, v4, v5
	v_cvt_i32_f32_e32 v5, v6
	v_exp_f32_e32 v4, v4
	v_cmp_nlt_f32_e64 s[82:83], s74, v2
	v_ldexp_f32 v4, v4, v5
	s_nop 0
	v_cndmask_b32_e64 v4, 0, v4, s[82:83]
	v_cmp_ngt_f32_e64 s[82:83], s75, v2
	v_mov_b32_e32 v6, 0x7f800000
	s_nop 0
	v_cndmask_b32_e64 v3, v6, v4, s[82:83]
	v_sub_f32_e32 v3, 1.0, v3
	v_mul_f32_e32 v4, v0, v0
	v_mov_b32_e32 v6, s76
	v_fmamk_f32 v5, v4, 0xba1345e1, v6
	v_fmaak_f32 v5, v4, v5, 0xbcdac9b8
	v_fmaak_f32 v5, v4, v5, 0x3de703be
	v_fmaak_f32 v5, v4, v5, 0xbec09330
	v_fmaak_f32 v4, v4, v5, 0x3e0375d0
	v_fma_f32 v7, |v0|, v4, |v0|
	v_cmp_nlt_f32_e64 s[82:83], |v0|, 1.0
	s_nop 1
	v_cndmask_b32_e64 v3, v7, v3, s[82:83]
	v_bfi_b32 v3, s77, v3, v0
	v_mul_f32_e32 v144, 0.5, v144
	v_add_f32_e32 v3, 1.0, v3
	v_mul_f32_e32 v144, v144, v3
	v_mul_f32_e32 v144, v144, v148
	v_mul_f32_e32 v144, v152, v144
	v_mul_f32_e32 v145, v151, v145
	v_mul_f32_e32 v0, 0x3f3504f3, v145
	v_mov_b32_e32 v6, s67
	v_fma_f32 v2, |v0|, s66, v6
	v_fma_f32 v2, |v0|, v2, s68
	v_fma_f32 v2, |v0|, v2, s69
	v_fma_f32 v2, |v0|, v2, s70
	v_fma_f32 v2, |v0|, v2, s71
	v_fma_f32 v2, |v0|, v2, s72
	v_fma_f32 v2, |v0|, v2, |v0|
	v_mul_f32_e32 v4, 0xbfb8aa3b, v2
	v_fma_f32 v5, v2, s73, -v4
	v_rndne_f32_e32 v6, v4
	v_fmac_f32_e32 v5, 0xb2a5705f, v2
	v_sub_f32_e32 v4, v4, v6
	v_add_f32_e32 v4, v4, v5
	v_cvt_i32_f32_e32 v5, v6
	v_exp_f32_e32 v4, v4
	v_cmp_nlt_f32_e64 s[82:83], s74, v2
	v_ldexp_f32 v4, v4, v5
	s_nop 0
	v_cndmask_b32_e64 v4, 0, v4, s[82:83]
	v_cmp_ngt_f32_e64 s[82:83], s75, v2
	v_mov_b32_e32 v6, 0x7f800000
	s_nop 0
	v_cndmask_b32_e64 v3, v6, v4, s[82:83]
	v_sub_f32_e32 v3, 1.0, v3
	v_mul_f32_e32 v4, v0, v0
	v_mov_b32_e32 v6, s76
	v_fmamk_f32 v5, v4, 0xba1345e1, v6
	v_fmaak_f32 v5, v4, v5, 0xbcdac9b8
	v_fmaak_f32 v5, v4, v5, 0x3de703be
	v_fmaak_f32 v5, v4, v5, 0xbec09330
	v_fmaak_f32 v4, v4, v5, 0x3e0375d0
	v_fma_f32 v7, |v0|, v4, |v0|
	v_cmp_nlt_f32_e64 s[82:83], |v0|, 1.0
	s_nop 1
	v_cndmask_b32_e64 v3, v7, v3, s[82:83]
	v_bfi_b32 v3, s77, v3, v0
	v_mul_f32_e32 v145, 0.5, v145
	v_add_f32_e32 v3, 1.0, v3
	v_mul_f32_e32 v145, v145, v3
	v_mul_f32_e32 v145, v145, v149
	v_mul_f32_e32 v145, v153, v145
	ds_write_b64 v222, v[144:145] offset:6144
	v_mul_f32_e32 v156, v162, v156
	v_mul_f32_e32 v0, 0x3f3504f3, v156
	v_mov_b32_e32 v6, s67
	v_fma_f32 v2, |v0|, s66, v6
	v_fma_f32 v2, |v0|, v2, s68
	v_fma_f32 v2, |v0|, v2, s69
	v_fma_f32 v2, |v0|, v2, s70
	v_fma_f32 v2, |v0|, v2, s71
	v_fma_f32 v2, |v0|, v2, s72
	v_fma_f32 v2, |v0|, v2, |v0|
	v_mul_f32_e32 v4, 0xbfb8aa3b, v2
	v_fma_f32 v5, v2, s73, -v4
	v_rndne_f32_e32 v6, v4
	v_fmac_f32_e32 v5, 0xb2a5705f, v2
	v_sub_f32_e32 v4, v4, v6
	v_add_f32_e32 v4, v4, v5
	v_cvt_i32_f32_e32 v5, v6
	v_exp_f32_e32 v4, v4
	v_cmp_nlt_f32_e64 s[82:83], s74, v2
	v_ldexp_f32 v4, v4, v5
	s_nop 0
	v_cndmask_b32_e64 v4, 0, v4, s[82:83]
	v_cmp_ngt_f32_e64 s[82:83], s75, v2
	v_mov_b32_e32 v6, 0x7f800000
	s_nop 0
	v_cndmask_b32_e64 v3, v6, v4, s[82:83]
	v_sub_f32_e32 v3, 1.0, v3
	v_mul_f32_e32 v4, v0, v0
	v_mov_b32_e32 v6, s76
	v_fmamk_f32 v5, v4, 0xba1345e1, v6
	v_fmaak_f32 v5, v4, v5, 0xbcdac9b8
	v_fmaak_f32 v5, v4, v5, 0x3de703be
	v_fmaak_f32 v5, v4, v5, 0xbec09330
	v_fmaak_f32 v4, v4, v5, 0x3e0375d0
	v_fma_f32 v7, |v0|, v4, |v0|
	v_cmp_nlt_f32_e64 s[82:83], |v0|, 1.0
	s_nop 1
	v_cndmask_b32_e64 v3, v7, v3, s[82:83]
	v_bfi_b32 v3, s77, v3, v0
	v_mul_f32_e32 v156, 0.5, v156
	v_add_f32_e32 v3, 1.0, v3
	v_mul_f32_e32 v156, v156, v3
	v_mul_f32_e32 v156, v156, v160
	v_mul_f32_e32 v156, v164, v156
	v_mul_f32_e32 v157, v163, v157
	v_mul_f32_e32 v0, 0x3f3504f3, v157
	v_mov_b32_e32 v6, s67
	v_fma_f32 v2, |v0|, s66, v6
	v_fma_f32 v2, |v0|, v2, s68
	v_fma_f32 v2, |v0|, v2, s69
	v_fma_f32 v2, |v0|, v2, s70
	v_fma_f32 v2, |v0|, v2, s71
	v_fma_f32 v2, |v0|, v2, s72
	v_fma_f32 v2, |v0|, v2, |v0|
	v_mul_f32_e32 v4, 0xbfb8aa3b, v2
	v_fma_f32 v5, v2, s73, -v4
	v_rndne_f32_e32 v6, v4
	v_fmac_f32_e32 v5, 0xb2a5705f, v2
	v_sub_f32_e32 v4, v4, v6
	v_add_f32_e32 v4, v4, v5
	v_cvt_i32_f32_e32 v5, v6
	v_exp_f32_e32 v4, v4
	v_cmp_nlt_f32_e64 s[82:83], s74, v2
	v_ldexp_f32 v4, v4, v5
	s_nop 0
	v_cndmask_b32_e64 v4, 0, v4, s[82:83]
	v_cmp_ngt_f32_e64 s[82:83], s75, v2
	v_mov_b32_e32 v6, 0x7f800000
	s_nop 0
	v_cndmask_b32_e64 v3, v6, v4, s[82:83]
	v_sub_f32_e32 v3, 1.0, v3
	v_mul_f32_e32 v4, v0, v0
	v_mov_b32_e32 v6, s76
	v_fmamk_f32 v5, v4, 0xba1345e1, v6
	v_fmaak_f32 v5, v4, v5, 0xbcdac9b8
	v_fmaak_f32 v5, v4, v5, 0x3de703be
	v_fmaak_f32 v5, v4, v5, 0xbec09330
	v_fmaak_f32 v4, v4, v5, 0x3e0375d0
	v_fma_f32 v7, |v0|, v4, |v0|
	v_cmp_nlt_f32_e64 s[82:83], |v0|, 1.0
	s_nop 1
	v_cndmask_b32_e64 v3, v7, v3, s[82:83]
	v_bfi_b32 v3, s77, v3, v0
	v_mul_f32_e32 v157, 0.5, v157
	v_add_f32_e32 v3, 1.0, v3
	v_mul_f32_e32 v157, v157, v3
	v_mul_f32_e32 v157, v157, v161
	v_mul_f32_e32 v157, v165, v157
	ds_write_b64 v222, v[156:157] offset:6656
	v_mul_f32_e32 v168, v174, v168
	v_mul_f32_e32 v0, 0x3f3504f3, v168
	v_mov_b32_e32 v6, s67
	v_fma_f32 v2, |v0|, s66, v6
	v_fma_f32 v2, |v0|, v2, s68
	v_fma_f32 v2, |v0|, v2, s69
	v_fma_f32 v2, |v0|, v2, s70
	v_fma_f32 v2, |v0|, v2, s71
	v_fma_f32 v2, |v0|, v2, s72
	v_fma_f32 v2, |v0|, v2, |v0|
	v_mul_f32_e32 v4, 0xbfb8aa3b, v2
	v_fma_f32 v5, v2, s73, -v4
	v_rndne_f32_e32 v6, v4
	v_fmac_f32_e32 v5, 0xb2a5705f, v2
	v_sub_f32_e32 v4, v4, v6
	v_add_f32_e32 v4, v4, v5
	v_cvt_i32_f32_e32 v5, v6
	v_exp_f32_e32 v4, v4
	v_cmp_nlt_f32_e64 s[82:83], s74, v2
	v_ldexp_f32 v4, v4, v5
	s_nop 0
	v_cndmask_b32_e64 v4, 0, v4, s[82:83]
	v_cmp_ngt_f32_e64 s[82:83], s75, v2
	v_mov_b32_e32 v6, 0x7f800000
	s_nop 0
	v_cndmask_b32_e64 v3, v6, v4, s[82:83]
	v_sub_f32_e32 v3, 1.0, v3
	v_mul_f32_e32 v4, v0, v0
	v_mov_b32_e32 v6, s76
	v_fmamk_f32 v5, v4, 0xba1345e1, v6
	v_fmaak_f32 v5, v4, v5, 0xbcdac9b8
	v_fmaak_f32 v5, v4, v5, 0x3de703be
	v_fmaak_f32 v5, v4, v5, 0xbec09330
	v_fmaak_f32 v4, v4, v5, 0x3e0375d0
	v_fma_f32 v7, |v0|, v4, |v0|
	v_cmp_nlt_f32_e64 s[82:83], |v0|, 1.0
	s_nop 1
	v_cndmask_b32_e64 v3, v7, v3, s[82:83]
	v_bfi_b32 v3, s77, v3, v0
	v_mul_f32_e32 v168, 0.5, v168
	v_add_f32_e32 v3, 1.0, v3
	v_mul_f32_e32 v168, v168, v3
	v_mul_f32_e32 v168, v168, v172
	v_mul_f32_e32 v168, v176, v168
	v_mul_f32_e32 v169, v175, v169
	v_mul_f32_e32 v0, 0x3f3504f3, v169
	v_mov_b32_e32 v6, s67
	v_fma_f32 v2, |v0|, s66, v6
	v_fma_f32 v2, |v0|, v2, s68
	v_fma_f32 v2, |v0|, v2, s69
	v_fma_f32 v2, |v0|, v2, s70
	v_fma_f32 v2, |v0|, v2, s71
	v_fma_f32 v2, |v0|, v2, s72
	v_fma_f32 v2, |v0|, v2, |v0|
	v_mul_f32_e32 v4, 0xbfb8aa3b, v2
	v_fma_f32 v5, v2, s73, -v4
	v_rndne_f32_e32 v6, v4
	v_fmac_f32_e32 v5, 0xb2a5705f, v2
	v_sub_f32_e32 v4, v4, v6
	v_add_f32_e32 v4, v4, v5
	v_cvt_i32_f32_e32 v5, v6
	v_exp_f32_e32 v4, v4
	v_cmp_nlt_f32_e64 s[82:83], s74, v2
	v_ldexp_f32 v4, v4, v5
	s_nop 0
	v_cndmask_b32_e64 v4, 0, v4, s[82:83]
	v_cmp_ngt_f32_e64 s[82:83], s75, v2
	v_mov_b32_e32 v6, 0x7f800000
	s_nop 0
	v_cndmask_b32_e64 v3, v6, v4, s[82:83]
	v_sub_f32_e32 v3, 1.0, v3
	v_mul_f32_e32 v4, v0, v0
	v_mov_b32_e32 v6, s76
	v_fmamk_f32 v5, v4, 0xba1345e1, v6
	v_fmaak_f32 v5, v4, v5, 0xbcdac9b8
	v_fmaak_f32 v5, v4, v5, 0x3de703be
	v_fmaak_f32 v5, v4, v5, 0xbec09330
	v_fmaak_f32 v4, v4, v5, 0x3e0375d0
	v_fma_f32 v7, |v0|, v4, |v0|
	v_cmp_nlt_f32_e64 s[82:83], |v0|, 1.0
	s_nop 1
	v_cndmask_b32_e64 v3, v7, v3, s[82:83]
	v_bfi_b32 v3, s77, v3, v0
	v_mul_f32_e32 v169, 0.5, v169
	v_add_f32_e32 v3, 1.0, v3
	v_mul_f32_e32 v169, v169, v3
	v_mul_f32_e32 v169, v169, v173
	v_mul_f32_e32 v169, v177, v169
	ds_write_b64 v222, v[168:169] offset:7168
	v_mul_f32_e32 v180, v186, v180
	v_mul_f32_e32 v0, 0x3f3504f3, v180
	v_mov_b32_e32 v6, s67
	v_fma_f32 v2, |v0|, s66, v6
	v_fma_f32 v2, |v0|, v2, s68
	v_fma_f32 v2, |v0|, v2, s69
	v_fma_f32 v2, |v0|, v2, s70
	v_fma_f32 v2, |v0|, v2, s71
	v_fma_f32 v2, |v0|, v2, s72
	v_fma_f32 v2, |v0|, v2, |v0|
	v_mul_f32_e32 v4, 0xbfb8aa3b, v2
	v_fma_f32 v5, v2, s73, -v4
	v_rndne_f32_e32 v6, v4
	v_fmac_f32_e32 v5, 0xb2a5705f, v2
	v_sub_f32_e32 v4, v4, v6
	v_add_f32_e32 v4, v4, v5
	v_cvt_i32_f32_e32 v5, v6
	v_exp_f32_e32 v4, v4
	v_cmp_nlt_f32_e64 s[82:83], s74, v2
	v_ldexp_f32 v4, v4, v5
	s_nop 0
	v_cndmask_b32_e64 v4, 0, v4, s[82:83]
	v_cmp_ngt_f32_e64 s[82:83], s75, v2
	v_mov_b32_e32 v6, 0x7f800000
	s_nop 0
	v_cndmask_b32_e64 v3, v6, v4, s[82:83]
	v_sub_f32_e32 v3, 1.0, v3
	v_mul_f32_e32 v4, v0, v0
	v_mov_b32_e32 v6, s76
	v_fmamk_f32 v5, v4, 0xba1345e1, v6
	v_fmaak_f32 v5, v4, v5, 0xbcdac9b8
	v_fmaak_f32 v5, v4, v5, 0x3de703be
	v_fmaak_f32 v5, v4, v5, 0xbec09330
	v_fmaak_f32 v4, v4, v5, 0x3e0375d0
	v_fma_f32 v7, |v0|, v4, |v0|
	v_cmp_nlt_f32_e64 s[82:83], |v0|, 1.0
	s_nop 1
	v_cndmask_b32_e64 v3, v7, v3, s[82:83]
	v_bfi_b32 v3, s77, v3, v0
	v_mul_f32_e32 v180, 0.5, v180
	v_add_f32_e32 v3, 1.0, v3
	v_mul_f32_e32 v180, v180, v3
	v_mul_f32_e32 v180, v180, v184
	v_mul_f32_e32 v180, v188, v180
	v_mul_f32_e32 v181, v187, v181
	v_mul_f32_e32 v0, 0x3f3504f3, v181
	v_mov_b32_e32 v6, s67
	v_fma_f32 v2, |v0|, s66, v6
	v_fma_f32 v2, |v0|, v2, s68
	v_fma_f32 v2, |v0|, v2, s69
	v_fma_f32 v2, |v0|, v2, s70
	v_fma_f32 v2, |v0|, v2, s71
	v_fma_f32 v2, |v0|, v2, s72
	v_fma_f32 v2, |v0|, v2, |v0|
	v_mul_f32_e32 v4, 0xbfb8aa3b, v2
	v_fma_f32 v5, v2, s73, -v4
	v_rndne_f32_e32 v6, v4
	v_fmac_f32_e32 v5, 0xb2a5705f, v2
	v_sub_f32_e32 v4, v4, v6
	v_add_f32_e32 v4, v4, v5
	v_cvt_i32_f32_e32 v5, v6
	v_exp_f32_e32 v4, v4
	v_cmp_nlt_f32_e64 s[82:83], s74, v2
	v_ldexp_f32 v4, v4, v5
	s_nop 0
	v_cndmask_b32_e64 v4, 0, v4, s[82:83]
	v_cmp_ngt_f32_e64 s[82:83], s75, v2
	v_mov_b32_e32 v6, 0x7f800000
	s_nop 0
	v_cndmask_b32_e64 v3, v6, v4, s[82:83]
	v_sub_f32_e32 v3, 1.0, v3
	v_mul_f32_e32 v4, v0, v0
	v_mov_b32_e32 v6, s76
	v_fmamk_f32 v5, v4, 0xba1345e1, v6
	v_fmaak_f32 v5, v4, v5, 0xbcdac9b8
	v_fmaak_f32 v5, v4, v5, 0x3de703be
	v_fmaak_f32 v5, v4, v5, 0xbec09330
	v_fmaak_f32 v4, v4, v5, 0x3e0375d0
	v_fma_f32 v7, |v0|, v4, |v0|
	v_cmp_nlt_f32_e64 s[82:83], |v0|, 1.0
	s_nop 1
	v_cndmask_b32_e64 v3, v7, v3, s[82:83]
	v_bfi_b32 v3, s77, v3, v0
	v_mul_f32_e32 v181, 0.5, v181
	v_add_f32_e32 v3, 1.0, v3
	v_mul_f32_e32 v181, v181, v3
	v_mul_f32_e32 v181, v181, v185
	v_mul_f32_e32 v181, v189, v181
	ds_write_b64 v222, v[180:181] offset:7680
	s_waitcnt lgkmcnt(0)
	s_mov_b32 s8, 8
	s_mov_b32 s7, 0
	s_mov_b32 s54, 8
	s_mov_b32 s53, 0
	s_mul_i32 s55, s53, s5
	s_add_i32 s55, s55, s6
	s_min_u32 s55, s55, 0x3fff
	s_and_b32 s34, s54, 7
	s_mul_i32 s34, s34, 0x300000
	s_cmp_lt_u32 s54, 8
	s_cselect_b32 s30, s16, s18
	s_cselect_b32 s31, s17, s19
	s_add_u32 s30, s30, s34
	s_addc_u32 s31, s31, 0
	s_and_b32 s34, s54, 7
	s_lshl_b32 s34, s34, 6
	s_lshl_b32 s35, s55, 12
	s_add_u32 s34, s34, s35
	s_add_u32 s32, s24, s34
	s_addc_u32 s33, s25, 0
	s_and_b32 s34, s54, 7
	s_lshl_b32 s34, s34, 7
	s_lshr_b32 s35, s55, 13
	s_mul_i32 s35, s35, 0xc000
	s_add_u32 s35, s35, s34
	s_add_u32 s35, s35, 0xa000
	s_add_u32 s58, s26, s35
	s_addc_u32 s59, s27, 0
	s_lshl_b32 s35, s55, 13
	s_add_u32 s35, s35, s34
	s_add_u32 s60, s28, s35
	s_addc_u32 s61, s29, 0
	s_mul_i32 s34, s53, s5
	s_add_i32 s34, s34, s6
	s_cmp_lt_u32 s34, 0x4000
	s_cselect_b32 s57, 1, 0
	s_mov_b32 s78, s60
	s_mov_b32 s79, s61
	s_mov_b32 s80, s57
	s_lshl_b32 s34, s53, 9
	v_add_u32_e32 v216, s34, v223
	ds_read_b128 v[80:83], v216 offset:0
	ds_read_b128 v[84:87], v216 offset:16
	ds_read_b128 v[88:91], v216 offset:32
	ds_read_b128 v[92:95], v216 offset:48
	s_waitcnt lgkmcnt(0)
	global_load_dwordx2 v[64:65], v225, s[32:33]
	global_load_dwordx4 v[66:69], v226, s[58:59]
	v_mad_u32_u24 v217, v80, s52, v220
	v_add_u32_e32 v218, v217, v221
	global_load_dwordx4 v[96:99], v217, s[30:31]
	global_load_dwordx2 v[100:101], v218, s[30:31]
	v_mad_u32_u24 v217, v81, s52, v220
	v_add_u32_e32 v218, v217, v221
	global_load_dwordx4 v[102:105], v217, s[30:31]
	global_load_dwordx2 v[106:107], v218, s[30:31]
	v_mad_u32_u24 v217, v82, s52, v220
	v_add_u32_e32 v218, v217, v221
	global_load_dwordx4 v[108:111], v217, s[30:31]
	global_load_dwordx2 v[112:113], v218, s[30:31]
	v_mad_u32_u24 v217, v83, s52, v220
	v_add_u32_e32 v218, v217, v221
	global_load_dwordx4 v[114:117], v217, s[30:31]
	global_load_dwordx2 v[118:119], v218, s[30:31]
	v_mad_u32_u24 v217, v84, s52, v220
	v_add_u32_e32 v218, v217, v221
	global_load_dwordx4 v[120:123], v217, s[30:31]
	global_load_dwordx2 v[124:125], v218, s[30:31]
	v_mad_u32_u24 v217, v85, s52, v220
	v_add_u32_e32 v218, v217, v221
	global_load_dwordx4 v[126:129], v217, s[30:31]
	global_load_dwordx2 v[130:131], v218, s[30:31]
	v_mad_u32_u24 v217, v86, s52, v220
	v_add_u32_e32 v218, v217, v221
	global_load_dwordx4 v[132:135], v217, s[30:31]
	global_load_dwordx2 v[136:137], v218, s[30:31]
	v_mad_u32_u24 v217, v87, s52, v220
	v_add_u32_e32 v218, v217, v221
	global_load_dwordx4 v[138:141], v217, s[30:31]
	global_load_dwordx2 v[142:143], v218, s[30:31]
	v_mad_u32_u24 v217, v88, s52, v220
	v_add_u32_e32 v218, v217, v221
	global_load_dwordx4 v[144:147], v217, s[30:31]
	global_load_dwordx2 v[148:149], v218, s[30:31]
	v_mad_u32_u24 v217, v89, s52, v220
	v_add_u32_e32 v218, v217, v221
	global_load_dwordx4 v[150:153], v217, s[30:31]
	global_load_dwordx2 v[154:155], v218, s[30:31]
	v_mad_u32_u24 v217, v90, s52, v220
	v_add_u32_e32 v218, v217, v221
	global_load_dwordx4 v[156:159], v217, s[30:31]
	global_load_dwordx2 v[160:161], v218, s[30:31]
	v_mad_u32_u24 v217, v91, s52, v220
	v_add_u32_e32 v218, v217, v221
	global_load_dwordx4 v[162:165], v217, s[30:31]
	global_load_dwordx2 v[166:167], v218, s[30:31]
	v_mad_u32_u24 v217, v92, s52, v220
	v_add_u32_e32 v218, v217, v221
	global_load_dwordx4 v[168:171], v217, s[30:31]
	global_load_dwordx2 v[172:173], v218, s[30:31]
	v_mad_u32_u24 v217, v93, s52, v220
	v_add_u32_e32 v218, v217, v221
	global_load_dwordx4 v[174:177], v217, s[30:31]
	global_load_dwordx2 v[178:179], v218, s[30:31]
	v_mad_u32_u24 v217, v94, s52, v220
	v_add_u32_e32 v218, v217, v221
	global_load_dwordx4 v[180:183], v217, s[30:31]
	global_load_dwordx2 v[184:185], v218, s[30:31]
	v_mad_u32_u24 v217, v95, s52, v220
	v_add_u32_e32 v218, v217, v221
	global_load_dwordx4 v[186:189], v217, s[30:31]
	global_load_dwordx2 v[190:191], v218, s[30:31]
	global_load_dword v233, v231, s[28:29]
	s_add_i32 s53, s7, 1
	s_mov_b32 s54, s8
	s_cmp_eq_u32 s53, 8
	s_cselect_b32 s53, 0, s53
	s_cselect_b32 s34, 1, 0
	s_add_i32 s54, s54, s34
	s_mul_i32 s55, s53, s5
	s_add_i32 s55, s55, s6
	s_min_u32 s55, s55, 0x3fff
	s_and_b32 s34, s54, 7
	s_mul_i32 s34, s34, 0x300000
	s_cmp_lt_u32 s54, 8
	s_cselect_b32 s30, s16, s18
	s_cselect_b32 s31, s17, s19
	s_add_u32 s30, s30, s34
	s_addc_u32 s31, s31, 0
	s_and_b32 s34, s54, 7
	s_lshl_b32 s34, s34, 6
	s_lshl_b32 s35, s55, 12
	s_add_u32 s34, s34, s35
	s_add_u32 s32, s24, s34
	s_addc_u32 s33, s25, 0
	s_and_b32 s34, s54, 7
	s_lshl_b32 s34, s34, 7
	s_lshr_b32 s35, s55, 13
	s_mul_i32 s35, s35, 0xc000
	s_add_u32 s35, s35, s34
	s_add_u32 s35, s35, 0xa000
	s_add_u32 s58, s26, s35
	s_addc_u32 s59, s27, 0
	s_lshl_b32 s35, s55, 13
	s_add_u32 s35, s35, s34
	s_add_u32 s60, s28, s35
	s_addc_u32 s61, s29, 0
	s_mul_i32 s34, s53, s5
	s_add_i32 s34, s34, s6
	s_cmp_lt_u32 s34, 0x4000
	s_cselect_b32 s57, 1, 0
	s_lshl_b32 s34, s53, 9
	v_add_u32_e32 v216, s34, v223
	ds_read_b128 v[80:83], v216 offset:0
	ds_read_b128 v[84:87], v216 offset:16
	ds_read_b128 v[88:91], v216 offset:32
	ds_read_b128 v[92:95], v216 offset:48

.Lex_vskip:
	global_load_dword v233, v231, s[28:29]
